# pool item: the four LDS reads of each column tile issued ahead of its MFMAs
# speedup vs baseline: 1.0008x; 1.0008x over previous
; template <int W>
; DI void pool_fill(LAS bf16_t* dA, const Args& a, int l, int g, int t0, int tid) {
;     ...
;             const f32x4 d = sum * inv - pv[j + W - 1]; u32x2 pw; pw.x = pk2(d[0], d[1]); pw.y = pk2(d[2], d[3]); *(LAS u32x2*)(dA + (lr0 + j) * 136 + c0) = pw; }
;     } else {
; #pragma unroll
;         for (int j = 0; j < 8; ++j) { const int row = row0 + j; const bf16_t* pp = PROJ + (size_t)row * NPROJ + 2048 + g * 128 + c0;
;             const u32x2 raw = *(const u32x2*)pp; const f32x4 p0 = {bflo(raw.x), bfhi(raw.x), bflo(raw.y), bfhi(raw.y)}; f32x4 sum = p0;
;             const float* sp = INP(a, 4) + (size_t)(l * 128 + (row - NPROMPT)) * 15 * 512 + g * 128 + c0;
; #pragma unroll
;             for (int i = 1; i < W; ++i) sum += *(const f32x4*)(sp + (size_t)(15 - i) * 512);
;             const f32x4 d = sum * (1.f / (float)W) - p0; u32x2 pw; pw.x = pk2(d[0], d[1]); pw.y = pk2(d[2], d[3]); *(LAS u32x2*)(dA + (lr0 + j) * 136 + c0) = pw; }
;     }
; }
; DI void pool_item(LAS unsigned char* lds, const Args& a, int l, int item) {
;     int tid_ = threadIdx.x; asm volatile("" : "+v"(tid_));
;     const int tid = tid_, g = item & 3, rt = item >> 2, t0 = rt * 128;
;     LAS bf16_t* dA = (LAS bf16_t*)lds; LAS bf16_t* wB = dA + 128 * 136;
;     const bf16_t* PW = (const bf16_t*)(a.ws + WS_W + (size_t)l * W_LSTRIDE + WO_PW) + (size_t)g * 16384;
;     for (int e = tid; e < 2048; e += 512) { const int r = e >> 4, c8 = (e & 15) * 8; *(LAS u32x4*)(wB + r * 136 + c8) = *(const u32x4*)(PW + r * 128 + c8); }
;     if (g == 0) pool_fill<2>(dA, a, l, g, t0, tid); else if (g == 1) pool_fill<4>(dA, a, l, g, t0, tid); else if (g == 2) pool_fill<8>(dA, a, l, g, t0, tid); else pool_fill<16>(dA, a, l, g, t0, tid);
;     __syncthreads();
;     { const int w8 = tid >> 6, lane = tid & 63, fr = lane & 15, fq = lane >> 4;
;       bf16x8 af[4];
; #pragma unroll
;       for (int ks = 0; ks < 4; ++ks) af[ks] = *(const LAS bf16x8*)(dA + (16 * w8 + fr) * 136 + 32 * ks + 8 * fq);
;       bf16_t* MIX = (bf16_t*)(a.ws + WS_MIX); const float* psc = INP(a, 16) + l * 512 + g * 128;
; #pragma unroll
;       for (int nt = 0; nt < 8; ++nt) { f32x4 acc = {0.f, 0.f, 0.f, 0.f};
; #pragma unroll
;           for (int ks = 0; ks < 4; ++ks) { const bf16x8 bb = *(const LAS bf16x8*)(wB + (16 * nt + fr) * 136 + 32 * ks + 8 * fq); acc = MFMA16(af[ks], bb, acc); }
.LBB0_201:
	s_nop 0
	v_cvt_pk_bf16_f32 v0, v0, v1
	v_cvt_pk_bf16_f32 v1, v2, v3
	v_or_b32_e32 v2, 7, v89
	v_lshlrev_b32_e32 v4, 1, v90
	v_mul_lo_u32 v2, v2, s47
	v_add3_u32 v2, 0, v4, v2
	v_bfe_u32 v17, v88, 4, 2
	ds_write_b64 v2, v[0:1]
	v_bfi_b32 v0, -16, v89, v88
	v_lshl_add_u32 v16, v17, 4, 0
	v_mad_u64_u32 v[0:1], s[8:9], v0, s47, v[16:17]
	s_mov_b32 s8, 16
	s_waitcnt lgkmcnt(0)
	s_barrier
	ds_read_b128 v[12:15], v0
	ds_read_b128 v[8:11], v0 offset:64
	ds_read_b128 v[4:7], v0 offset:128
	ds_read_b128 v[0:3], v0 offset:192
	s_ashr_i32 s9, s8, 31
	s_lshl_b64 s[8:9], s[8:9], 3
	s_add_u32 s8, s0, s8
	s_addc_u32 s9, s1, s9
	s_load_dwordx2 s[8:9], s[8:9], 0x0
	s_lshl_b64 s[12:13], s[10:11], 2
	v_and_b32_e32 v27, 15, v88
	v_lshlrev_b32_e32 v24, 2, v27
	v_and_b32_e32 v18, -16, v89
	s_waitcnt lgkmcnt(0)
	s_add_u32 s8, s8, s12
	s_addc_u32 s9, s9, s13
	s_lshl_b32 s12, s16, 9
	s_add_u32 s8, s8, s12
	s_addc_u32 s9, s9, 0
	global_load_dword v40, v24, s[8:9]
	global_load_dword v41, v24, s[8:9] offset:64
	global_load_dword v42, v24, s[8:9] offset:128
	global_load_dword v43, v24, s[8:9] offset:192
	global_load_dword v44, v24, s[8:9] offset:256
	global_load_dword v45, v24, s[8:9] offset:320
	global_load_dword v46, v24, s[8:9] offset:384
	global_load_dword v47, v24, s[8:9] offset:448
	v_add_u32_e32 v18, s17, v18
	v_mad_u32_u24 v25, v27, s47, v16
	v_lshl_or_b32 v26, v17, 2, v18
	ds_read_b128 v[16:19], v25 offset:34816
	ds_read_b128 v[20:23], v25 offset:34880
	s_waitcnt lgkmcnt(1)
	v_mfma_f32_16x16x32_bf16 v[16:19], v[12:15], v[16:19], 0
	s_lshl_b32 s12, s16, 8
	v_readlane_b32 s13, v254, 10
	s_add_u32 s12, s13, s12
	s_waitcnt lgkmcnt(0)
	v_mfma_f32_16x16x32_bf16 v[16:19], v[8:11], v[20:23], v[16:19]
	ds_read_b128 v[20:23], v25 offset:34944
	v_readlane_b32 s13, v254, 11
	s_addc_u32 s13, s13, 0
	s_waitcnt lgkmcnt(0)
	v_mfma_f32_16x16x32_bf16 v[16:19], v[4:7], v[20:23], v[16:19]
	ds_read_b128 v[20:23], v25 offset:35008
	v_lshlrev_b32_e32 v128, 1, v27
	v_ashrrev_i32_e32 v27, 31, v26
	s_waitcnt lgkmcnt(0)
	v_mfma_f32_16x16x32_bf16 v[20:23], v[0:3], v[20:23], v[16:19]
	v_lshl_add_u64 v[28:29], s[12:13], 0, v[128:129]
	s_waitcnt vmcnt(7)
	s_nop 5
	v_mul_f32_e32 v16, v40, v20
	v_cvt_pk_bf16_f32 v18, v16, s0
	v_lshlrev_b64 v[16:17], 11, v[26:27]
	v_lshl_add_u64 v[16:17], v[28:29], 0, v[16:17]
	global_store_short v[16:17], v18, off
	v_mul_f32_e32 v18, v40, v21
	v_cvt_pk_bf16_f32 v20, v18, s0
	v_or_b32_e32 v18, 1, v26
	v_ashrrev_i32_e32 v19, 31, v18
	v_lshlrev_b64 v[18:19], 11, v[18:19]
	v_lshl_add_u64 v[18:19], v[28:29], 0, v[18:19]
	global_store_short v[18:19], v20, off
	v_mul_f32_e32 v20, v40, v22
	v_cvt_pk_bf16_f32 v22, v20, s0
	v_or_b32_e32 v20, 2, v26
	v_ashrrev_i32_e32 v21, 31, v20
	v_lshlrev_b64 v[20:21], 11, v[20:21]
	v_lshl_add_u64 v[20:21], v[28:29], 0, v[20:21]
	global_store_short v[20:21], v22, off
	v_mul_f32_e32 v22, v40, v23
	v_cvt_pk_bf16_f32 v27, v22, s0
	v_or_b32_e32 v22, 3, v26
	v_ashrrev_i32_e32 v23, 31, v22
	v_lshlrev_b64 v[22:23], 11, v[22:23]
	v_lshl_add_u64 v[22:23], v[28:29], 0, v[22:23]
	global_store_short v[22:23], v27, off
	ds_read_b128 v[26:29], v25 offset:39168
	ds_read_b128 v[30:33], v25 offset:39232
	ds_read_b128 v[48:51], v25 offset:39296
	ds_read_b128 v[52:55], v25 offset:39360
	s_waitcnt lgkmcnt(3)
	v_mfma_f32_16x16x32_bf16 v[26:29], v[12:15], v[26:29], 0
	s_waitcnt lgkmcnt(2)
	v_mfma_f32_16x16x32_bf16 v[26:29], v[8:11], v[30:33], v[26:29]
	s_waitcnt lgkmcnt(1)
	v_mfma_f32_16x16x32_bf16 v[26:29], v[4:7], v[48:51], v[26:29]
	s_waitcnt lgkmcnt(0)
	v_mfma_f32_16x16x32_bf16 v[26:29], v[0:3], v[52:55], v[26:29]
	s_waitcnt vmcnt(10)
	s_nop 6
	v_mul_f32_e32 v26, v41, v26
	v_cvt_pk_bf16_f32 v26, v26, s0
	global_store_short v[16:17], v26, off offset:32
	v_mul_f32_e32 v26, v41, v27
	v_cvt_pk_bf16_f32 v26, v26, s0
	global_store_short v[18:19], v26, off offset:32
	v_mul_f32_e32 v26, v41, v28
	v_cvt_pk_bf16_f32 v26, v26, s0
	global_store_short v[20:21], v26, off offset:32
	v_mul_f32_e32 v26, v41, v29
	v_cvt_pk_bf16_f32 v26, v26, s0
	global_store_short v[22:23], v26, off offset:32
	ds_read_b128 v[26:29], v25 offset:43520
	ds_read_b128 v[30:33], v25 offset:43584
	ds_read_b128 v[48:51], v25 offset:43648
	ds_read_b128 v[52:55], v25 offset:43712
	s_waitcnt lgkmcnt(3)
	v_mfma_f32_16x16x32_bf16 v[26:29], v[12:15], v[26:29], 0
	s_waitcnt lgkmcnt(2)
	v_mfma_f32_16x16x32_bf16 v[26:29], v[8:11], v[30:33], v[26:29]
	s_waitcnt lgkmcnt(1)
	v_mfma_f32_16x16x32_bf16 v[26:29], v[4:7], v[48:51], v[26:29]
	s_waitcnt lgkmcnt(0)
	v_mfma_f32_16x16x32_bf16 v[26:29], v[0:3], v[52:55], v[26:29]
	s_waitcnt vmcnt(13)
	s_nop 6
	v_mul_f32_e32 v26, v42, v26
	v_cvt_pk_bf16_f32 v26, v26, s0
	global_store_short v[16:17], v26, off offset:64
	v_mul_f32_e32 v26, v42, v27
	v_cvt_pk_bf16_f32 v26, v26, s0
	global_store_short v[18:19], v26, off offset:64
	v_mul_f32_e32 v26, v42, v28
	v_cvt_pk_bf16_f32 v26, v26, s0
	global_store_short v[20:21], v26, off offset:64
	v_mul_f32_e32 v26, v42, v29
	v_cvt_pk_bf16_f32 v26, v26, s0
	global_store_short v[22:23], v26, off offset:64
	ds_read_b128 v[26:29], v25 offset:47872
	ds_read_b128 v[30:33], v25 offset:47936
	ds_read_b128 v[48:51], v25 offset:48000
	ds_read_b128 v[52:55], v25 offset:48064
	s_waitcnt lgkmcnt(3)
; #define LAS __attribute__((address_space(3)))
; DI bf16_t f2bf(float a) { return (bf16_t)(pk2(a, 0.f) & 0xffffu); }
; #define MFMA16(a, b, c) __builtin_amdgcn_mfma_f32_16x16x32_bf16((a), (b), (c), 0, 0, 0)
; DI void pool_item(LAS unsigned char* lds, const Args& a, int l, int item) {
;     ...
; #pragma unroll
;       for (int nt = 0; nt < 8; ++nt) { f32x4 acc = {0.f, 0.f, 0.f, 0.f};
; #pragma unroll
;           for (int ks = 0; ks < 4; ++ks) { const bf16x8 bb = *(const LAS bf16x8*)(wB + (16 * nt + fr) * 136 + 32 * ks + 8 * fq); acc = MFMA16(af[ks], bb, acc); }
;           const int col = 16 * nt + fr; const float sc = psc[col];
; #pragma unroll
;           for (int reg = 0; reg < 4; ++reg) MIX[(size_t)(t0 + 16 * w8 + 4 * fq + reg) * DM + 512 + g * 128 + col] = f2bf(acc[reg] * sc); } }
;     __syncthreads();
	v_mfma_f32_16x16x32_bf16 v[26:29], v[12:15], v[26:29], 0
	s_waitcnt lgkmcnt(2)
	v_mfma_f32_16x16x32_bf16 v[26:29], v[8:11], v[30:33], v[26:29]
	s_waitcnt lgkmcnt(1)
	v_mfma_f32_16x16x32_bf16 v[26:29], v[4:7], v[48:51], v[26:29]
	s_waitcnt lgkmcnt(0)
	v_mfma_f32_16x16x32_bf16 v[26:29], v[0:3], v[52:55], v[26:29]
	s_waitcnt vmcnt(16)
	s_nop 6
	v_mul_f32_e32 v26, v43, v26
	v_cvt_pk_bf16_f32 v26, v26, s0
	global_store_short v[16:17], v26, off offset:96
	v_mul_f32_e32 v26, v43, v27
	v_cvt_pk_bf16_f32 v26, v26, s0
	global_store_short v[18:19], v26, off offset:96
	v_mul_f32_e32 v26, v43, v28
	v_cvt_pk_bf16_f32 v26, v26, s0
	global_store_short v[20:21], v26, off offset:96
	v_mul_f32_e32 v26, v43, v29
	v_cvt_pk_bf16_f32 v26, v26, s0
	global_store_short v[22:23], v26, off offset:96
	ds_read_b128 v[26:29], v25 offset:52224
	ds_read_b128 v[30:33], v25 offset:52288
	ds_read_b128 v[48:51], v25 offset:52352
	ds_read_b128 v[52:55], v25 offset:52416
	s_waitcnt lgkmcnt(3)
	v_mfma_f32_16x16x32_bf16 v[26:29], v[12:15], v[26:29], 0
	s_waitcnt lgkmcnt(2)
	v_mfma_f32_16x16x32_bf16 v[26:29], v[8:11], v[30:33], v[26:29]
	s_waitcnt lgkmcnt(1)
	v_mfma_f32_16x16x32_bf16 v[26:29], v[4:7], v[48:51], v[26:29]
	s_waitcnt lgkmcnt(0)
	v_mfma_f32_16x16x32_bf16 v[26:29], v[0:3], v[52:55], v[26:29]
	s_waitcnt vmcnt(19)
	s_nop 6
	v_mul_f32_e32 v26, v44, v26
	v_cvt_pk_bf16_f32 v26, v26, s0
	global_store_short v[16:17], v26, off offset:128
	v_mul_f32_e32 v26, v44, v27
	v_cvt_pk_bf16_f32 v26, v26, s0
	global_store_short v[18:19], v26, off offset:128
	v_mul_f32_e32 v26, v44, v28
	v_cvt_pk_bf16_f32 v26, v26, s0
	global_store_short v[20:21], v26, off offset:128
	v_mul_f32_e32 v26, v44, v29
	v_cvt_pk_bf16_f32 v26, v26, s0
	global_store_short v[22:23], v26, off offset:128
	ds_read_b128 v[26:29], v25 offset:56576
	ds_read_b128 v[30:33], v25 offset:56640
	ds_read_b128 v[48:51], v25 offset:56704
	ds_read_b128 v[52:55], v25 offset:56768
	s_waitcnt lgkmcnt(3)
	v_mfma_f32_16x16x32_bf16 v[26:29], v[12:15], v[26:29], 0
	s_waitcnt lgkmcnt(2)
	v_mfma_f32_16x16x32_bf16 v[26:29], v[8:11], v[30:33], v[26:29]
	s_waitcnt lgkmcnt(1)
	v_mfma_f32_16x16x32_bf16 v[26:29], v[4:7], v[48:51], v[26:29]
	s_waitcnt lgkmcnt(0)
	v_mfma_f32_16x16x32_bf16 v[26:29], v[0:3], v[52:55], v[26:29]
	s_waitcnt vmcnt(22)
	s_nop 6
	v_mul_f32_e32 v26, v45, v26
	v_cvt_pk_bf16_f32 v26, v26, s0
	global_store_short v[16:17], v26, off offset:160
	v_mul_f32_e32 v26, v45, v27
	v_cvt_pk_bf16_f32 v26, v26, s0
	global_store_short v[18:19], v26, off offset:160
	v_mul_f32_e32 v26, v45, v28
	v_cvt_pk_bf16_f32 v26, v26, s0
	global_store_short v[20:21], v26, off offset:160
	v_mul_f32_e32 v26, v45, v29
	v_cvt_pk_bf16_f32 v26, v26, s0
	global_store_short v[22:23], v26, off offset:160
	ds_read_b128 v[26:29], v25 offset:60928
	ds_read_b128 v[30:33], v25 offset:60992
	ds_read_b128 v[48:51], v25 offset:61056
	ds_read_b128 v[52:55], v25 offset:61120
	s_waitcnt lgkmcnt(3)
	v_mfma_f32_16x16x32_bf16 v[26:29], v[12:15], v[26:29], 0
	s_waitcnt lgkmcnt(2)
	v_mfma_f32_16x16x32_bf16 v[26:29], v[8:11], v[30:33], v[26:29]
	s_waitcnt lgkmcnt(1)
	v_mfma_f32_16x16x32_bf16 v[26:29], v[4:7], v[48:51], v[26:29]
	s_waitcnt lgkmcnt(0)
	v_mfma_f32_16x16x32_bf16 v[26:29], v[0:3], v[52:55], v[26:29]
	s_waitcnt vmcnt(25)
	s_nop 6
	v_mul_f32_e32 v26, v46, v26
	v_cvt_pk_bf16_f32 v26, v26, s0
	global_store_short v[16:17], v26, off offset:192
	v_mul_f32_e32 v26, v46, v27
	v_cvt_pk_bf16_f32 v26, v26, s0
	global_store_short v[18:19], v26, off offset:192
	v_mul_f32_e32 v26, v46, v28
	v_cvt_pk_bf16_f32 v26, v26, s0
	global_store_short v[20:21], v26, off offset:192
	v_mul_f32_e32 v26, v46, v29
	v_cvt_pk_bf16_f32 v26, v26, s0
	global_store_short v[22:23], v26, off offset:192
	ds_read_b128 v[26:29], v25 offset:65280
	s_waitcnt lgkmcnt(0)
	v_mfma_f32_16x16x32_bf16 v[12:15], v[12:15], v[26:29], 0
	ds_read_b128 v[26:29], v25 offset:65344
	s_waitcnt lgkmcnt(0)
	v_mfma_f32_16x16x32_bf16 v[8:11], v[8:11], v[26:29], v[12:15]
	s_nop 4
	ds_read_b128 v[12:15], v25 offset:65408
	s_waitcnt lgkmcnt(0)
	v_mfma_f32_16x16x32_bf16 v[4:7], v[4:7], v[12:15], v[8:11]
	s_nop 2
	ds_read_b128 v[8:11], v25 offset:65472
	s_waitcnt lgkmcnt(0)
	v_mfma_f32_16x16x32_bf16 v[0:3], v[0:3], v[8:11], v[4:7]
	s_nop 2
	s_mov_b64 s[8:9], 0
	s_waitcnt vmcnt(28)
	s_nop 2
	v_mul_f32_e32 v0, v47, v0
	v_cvt_pk_bf16_f32 v0, v0, s0
	global_store_short v[16:17], v0, off offset:224
	v_mul_f32_e32 v0, v47, v1
	v_cvt_pk_bf16_f32 v0, v0, s0
	global_store_short v[18:19], v0, off offset:224
	v_mul_f32_e32 v0, v47, v2
	v_cvt_pk_bf16_f32 v0, v0, s0
	global_store_short v[20:21], v0, off offset:224
	v_mul_f32_e32 v0, v47, v3
	v_cvt_pk_bf16_f32 v0, v0, s0
	global_store_short v[22:23], v0, off offset:224
	s_barrier
